# conv phases store everything write-through (sc1), so the barrier after conv skips the L2 write-back
# baseline (speedup 1.0000x reference)
.LBB0_488:
	s_or_b64 exec, exec, s[14:15]
	v_add_u32_e32 v8, s12, v8
	v_cmp_lt_i32_e32 vcc, s19, v8
	global_store_dword v[2:3], v5, off sc1
	s_or_b64 s[10:11], vcc, s[10:11]
	v_lshl_add_u64 v[2:3], v[2:3], 0, s[8:9]
	s_andn2_b64 exec, exec, s[10:11]
	s_cbranch_execz .LBB0_491

.LBB0_491:
	s_or_b64 exec, exec, s[4:5]
	s_cmp_lt_i32 s61, 4
	s_cbranch_scc1 .LBB0_545
	s_waitcnt vmcnt(0) lgkmcnt(0)
	s_barrier
	v_readfirstlane_b32 s2, v162
	s_lshl_b32 s3, s33, 8
	s_add_u32 s6, s84, s3
	s_addc_u32 s7, s85, 0
	s_cmp_lg_u32 s2, 0
	s_cbranch_scc1 .Lgb3_wait
	s_mov_b64 s[8:9], exec
	s_mov_b64 exec, 1
	v_mov_b32_e32 v0, 0x12000
	ds_read_b64 v[2:3], v0
	v_mov_b32_e32 v0, 0x1400
	v_mov_b32_e32 v1, 1
	global_atomic_add v4, v0, v1, s[6:7] sc0
	s_mov_b32 s13, 0
	s_add_u32 s14, s84, 0x2480
	s_addc_u32 s15, s85, 0
	s_waitcnt lgkmcnt(0)
	v_readfirstlane_b32 s10, v2
	v_readfirstlane_b32 s11, v3
	v_mov_b32_e32 v0, 0
	s_nop 3
	s_mul_i32 s10, s10, 4
	s_mul_i32 s11, s11, 3
	s_waitcnt vmcnt(0)
	v_readfirstlane_b32 s12, v4
	s_nop 3
	s_add_u32 s12, s12, 1
	s_cmp_lg_u32 s12, s10
	s_cbranch_scc1 .Lgb3_poll
	global_atomic_add v0, v1, s[14:15] offset:0
	global_atomic_add v0, v1, s[14:15] offset:256
	global_atomic_add v0, v1, s[14:15] offset:512
	global_atomic_add v0, v1, s[14:15] offset:768
	global_atomic_add v0, v1, s[14:15] offset:1024
	global_atomic_add v0, v1, s[14:15] offset:1280
	global_atomic_add v0, v1, s[14:15] offset:1536
	global_atomic_add v0, v1, s[14:15] offset:1792
	global_atomic_add v0, v1, s[14:15] offset:2048
	global_atomic_add v0, v1, s[14:15] offset:2304
	global_atomic_add v0, v1, s[14:15] offset:2560
	global_atomic_add v0, v1, s[14:15] offset:2816
	global_atomic_add v0, v1, s[14:15] offset:3072
	global_atomic_add v0, v1, s[14:15] offset:3328
	global_atomic_add v0, v1, s[14:15] offset:3584
	global_atomic_add v0, v1, s[14:15] offset:3840
	v_mov_b32_e32 v0, 0x2480

.LBB0_1861:
	s_or_b64 exec, exec, s[14:15]
	v_add_u32_e32 v128, s8, v128
	v_cmp_lt_i32_e32 vcc, s19, v128
	global_store_dword v[2:3], v5, off sc1
	s_or_b64 s[12:13], vcc, s[12:13]
	v_lshl_add_u64 v[2:3], v[2:3], 0, s[10:11]
	s_andn2_b64 exec, exec, s[12:13]
	s_cbranch_execz .LBB0_1864

.LBB0_1864:
	s_or_b64 exec, exec, s[4:5]
	s_cmp_lt_i32 s61, 20
	s_cbranch_scc1 .LBB0_1918
	s_waitcnt vmcnt(0) lgkmcnt(0)
	s_barrier
	v_readfirstlane_b32 s2, v162
	s_lshl_b32 s3, s33, 8
	s_add_u32 s6, s84, s3
	s_addc_u32 s7, s85, 0
	s_cmp_lg_u32 s2, 0
	s_cbranch_scc1 .Lgb19_wait
	s_mov_b64 s[8:9], exec
	s_mov_b64 exec, 1
	v_mov_b32_e32 v0, 0x12000
	ds_read_b64 v[2:3], v0
	v_mov_b32_e32 v0, 0x1400
	v_mov_b32_e32 v1, 1
	global_atomic_add v4, v0, v1, s[6:7] sc0
	s_mov_b32 s13, 0
	s_add_u32 s14, s84, 0x2480
	s_addc_u32 s15, s85, 0
	s_waitcnt lgkmcnt(0)
	v_readfirstlane_b32 s10, v2
	v_readfirstlane_b32 s11, v3
	v_mov_b32_e32 v0, 0
	s_nop 3
	s_mul_i32 s10, s10, 16
	s_mul_i32 s11, s11, 15
	s_waitcnt vmcnt(0)
	v_readfirstlane_b32 s12, v4
	s_nop 3
	s_add_u32 s12, s12, 1
	s_cmp_lg_u32 s12, s10
	s_cbranch_scc1 .Lgb19_poll
	global_atomic_add v0, v1, s[14:15] offset:0
	global_atomic_add v0, v1, s[14:15] offset:256
	global_atomic_add v0, v1, s[14:15] offset:512
	global_atomic_add v0, v1, s[14:15] offset:768
	global_atomic_add v0, v1, s[14:15] offset:1024
	global_atomic_add v0, v1, s[14:15] offset:1280
	global_atomic_add v0, v1, s[14:15] offset:1536
	global_atomic_add v0, v1, s[14:15] offset:1792
	global_atomic_add v0, v1, s[14:15] offset:2048
	global_atomic_add v0, v1, s[14:15] offset:2304
	global_atomic_add v0, v1, s[14:15] offset:2560
	global_atomic_add v0, v1, s[14:15] offset:2816
	global_atomic_add v0, v1, s[14:15] offset:3072
	global_atomic_add v0, v1, s[14:15] offset:3328
	global_atomic_add v0, v1, s[14:15] offset:3584
	global_atomic_add v0, v1, s[14:15] offset:3840
	v_mov_b32_e32 v0, 0x2480
